# MFMA order per 32-segment in the 4 big GEMM loops: k-half major, A-fragment constant for 4 MFMAs, snake over B fragments (GLU loop untouched)
# baseline (speedup 1.0000x reference)
.LBB0_139:
	s_add_u32 s22, s18, 0xfff00080
	s_addc_u32 s23, s19, -1
	s_add_i32 s49, 0, 0x10000
	s_cmp_eq_u32 s48, 60
	s_cselect_b32 s25, s9, s23
	s_cselect_b32 s24, s44, s22
	s_cselect_b32 s23, s7, s47
	s_cselect_b32 s22, s45, s46
	s_add_i32 s52, 0, 0x14000
	v_add_u32_e32 v156, s49, v145
	v_add_u32_e32 v172, s52, v145
	ds_read_b128 v[140:143], v156
	ds_read_b128 v[148:151], v156 offset:1024
	ds_read_b128 v[152:155], v156 offset:2048
	ds_read_b128 v[156:159], v156 offset:3072
	ds_read_b128 v[160:163], v172
	ds_read_b128 v[164:167], v172 offset:1024
	ds_read_b128 v[168:171], v172 offset:2048
	ds_read_b128 v[190:193], v172 offset:3072
	v_lshl_add_u64 v[172:173], s[18:19], 0, v[136:137]
	s_add_i32 m0, s31, 0xc000
	ds_read_b128 v[194:197], v147
	ds_read_b128 v[198:201], v147 offset:1024
	ds_read_b128 v[202:205], v147 offset:2048
	ds_read_b128 v[206:209], v147 offset:3072
	ds_read_b128 v[228:231], v147 offset:4096
	ds_read_b128 v[232:235], v147 offset:5120
	ds_read_b128 v[236:239], v147 offset:6144
	ds_read_b128 v[240:243], v147 offset:7168
	global_load_lds_dwordx4 v[172:173], off
	v_lshl_add_u64 v[172:173], s[18:19], 0, v[138:139]
	s_add_i32 m0, s31, 0xe000
	s_nop 0
	global_load_lds_dwordx4 v[172:173], off
	s_waitcnt vmcnt(8)
	s_waitcnt lgkmcnt(0)
	s_barrier
	s_setprio 1
	s_waitcnt lgkmcnt(0)
	v_mfma_f32_16x16x32_bf16 v[126:129], v[140:143], v[194:197], v[126:129]
	v_mfma_f32_16x16x32_bf16 v[122:125], v[152:155], v[194:197], v[122:125]
	v_mfma_f32_16x16x32_bf16 v[114:117], v[160:163], v[194:197], v[114:117]
	v_mfma_f32_16x16x32_bf16 v[106:109], v[168:171], v[194:197], v[106:109]
	v_mfma_f32_16x16x32_bf16 v[90:93], v[168:171], v[202:205], v[90:93]
	v_mfma_f32_16x16x32_bf16 v[98:101], v[160:163], v[202:205], v[98:101]
	v_mfma_f32_16x16x32_bf16 v[110:113], v[152:155], v[202:205], v[110:113]
	v_mfma_f32_16x16x32_bf16 v[118:121], v[140:143], v[202:205], v[118:121]
	v_mfma_f32_16x16x32_bf16 v[102:105], v[140:143], v[228:231], v[102:105]
	v_mfma_f32_16x16x32_bf16 v[94:97], v[152:155], v[228:231], v[94:97]
	v_mfma_f32_16x16x32_bf16 v[82:85], v[160:163], v[228:231], v[82:85]
	v_mfma_f32_16x16x32_bf16 v[74:77], v[168:171], v[228:231], v[74:77]
	v_mfma_f32_16x16x32_bf16 v[66:69], v[168:171], v[236:239], v[66:69]
	v_mfma_f32_16x16x32_bf16 v[70:73], v[160:163], v[236:239], v[70:73]
	v_mfma_f32_16x16x32_bf16 v[78:81], v[152:155], v[236:239], v[78:81]
	v_mfma_f32_16x16x32_bf16 v[86:89], v[140:143], v[236:239], v[86:89]
	s_setprio 0
	s_setprio 1
	v_mfma_f32_16x16x32_bf16 v[126:129], v[148:151], v[198:201], v[126:129]
	v_mfma_f32_16x16x32_bf16 v[122:125], v[156:159], v[198:201], v[122:125]
	v_mfma_f32_16x16x32_bf16 v[114:117], v[164:167], v[198:201], v[114:117]
	v_mfma_f32_16x16x32_bf16 v[106:109], v[190:193], v[198:201], v[106:109]
	v_mfma_f32_16x16x32_bf16 v[90:93], v[190:193], v[206:209], v[90:93]
	v_mfma_f32_16x16x32_bf16 v[98:101], v[164:167], v[206:209], v[98:101]
	v_mfma_f32_16x16x32_bf16 v[110:113], v[156:159], v[206:209], v[110:113]
	v_mfma_f32_16x16x32_bf16 v[118:121], v[148:151], v[206:209], v[118:121]
	v_mfma_f32_16x16x32_bf16 v[102:105], v[148:151], v[232:235], v[102:105]
	v_mfma_f32_16x16x32_bf16 v[94:97], v[156:159], v[232:235], v[94:97]
	v_mfma_f32_16x16x32_bf16 v[82:85], v[164:167], v[232:235], v[82:85]
	v_mfma_f32_16x16x32_bf16 v[74:77], v[190:193], v[232:235], v[74:77]
	v_mfma_f32_16x16x32_bf16 v[66:69], v[190:193], v[240:243], v[66:69]
	v_mfma_f32_16x16x32_bf16 v[70:73], v[164:167], v[240:243], v[70:73]
	v_mfma_f32_16x16x32_bf16 v[78:81], v[156:159], v[240:243], v[78:81]
	v_mfma_f32_16x16x32_bf16 v[86:89], v[148:151], v[240:243], v[86:89]
	s_setprio 0
	s_barrier
	s_add_i32 s49, s49, s26
	v_lshl_add_u64 v[172:173], s[22:23], 0, v[0:1]
	s_mov_b32 m0, s49
	ds_read_b128 v[194:197], v147 offset:16384
	ds_read_b128 v[198:201], v147 offset:17408
	ds_read_b128 v[202:205], v147 offset:18432
	ds_read_b128 v[206:209], v147 offset:19456
	ds_read_b128 v[228:231], v147 offset:20480
	ds_read_b128 v[232:235], v147 offset:21504
	ds_read_b128 v[236:239], v147 offset:22528
	ds_read_b128 v[240:243], v147 offset:23552
	global_load_lds_dwordx4 v[172:173], off
	s_add_i32 m0, s49, 0x2000
	s_add_u32 s50, s22, 0x100000
	v_lshl_add_u64 v[178:179], s[22:23], 0, v[130:131]
	s_addc_u32 s51, s23, 0
	s_add_i32 s49, s52, s26
	global_load_lds_dwordx4 v[178:179], off
	v_lshl_add_u64 v[180:181], s[50:51], 0, v[0:1]
	s_mov_b32 m0, s49
	v_lshl_add_u64 v[210:211], s[24:25], 0, v[132:133]
	global_load_lds_dwordx4 v[180:181], off
	v_lshl_add_u64 v[180:181], s[50:51], 0, v[130:131]
	s_add_i32 m0, s49, 0x2000
	s_nop 0
	global_load_lds_dwordx4 v[180:181], off
	v_lshl_add_u64 v[180:181], s[24:25], 0, v[134:135]
	s_mov_b32 m0, s31
	s_nop 0
	global_load_lds_dwordx4 v[180:181], off
	s_mov_b32 m0, s36
	s_nop 0
	global_load_lds_dwordx4 v[210:211], off
	s_waitcnt vmcnt(8)
	s_waitcnt lgkmcnt(0)
	s_barrier
	s_setprio 1
	s_waitcnt lgkmcnt(0)
	v_mfma_f32_16x16x32_bf16 v[62:65], v[140:143], v[194:197], v[62:65]
	v_mfma_f32_16x16x32_bf16 v[58:61], v[152:155], v[194:197], v[58:61]
	v_mfma_f32_16x16x32_bf16 v[50:53], v[160:163], v[194:197], v[50:53]
	v_mfma_f32_16x16x32_bf16 v[42:45], v[168:171], v[194:197], v[42:45]
	v_mfma_f32_16x16x32_bf16 v[26:29], v[168:171], v[202:205], v[26:29]
	v_mfma_f32_16x16x32_bf16 v[34:37], v[160:163], v[202:205], v[34:37]
	v_mfma_f32_16x16x32_bf16 v[46:49], v[152:155], v[202:205], v[46:49]
	v_mfma_f32_16x16x32_bf16 v[54:57], v[140:143], v[202:205], v[54:57]
	v_mfma_f32_16x16x32_bf16 v[38:41], v[140:143], v[228:231], v[38:41]
	v_mfma_f32_16x16x32_bf16 v[30:33], v[152:155], v[228:231], v[30:33]
	v_mfma_f32_16x16x32_bf16 v[18:21], v[160:163], v[228:231], v[18:21]
	v_mfma_f32_16x16x32_bf16 v[10:13], v[168:171], v[228:231], v[10:13]
	v_mfma_f32_16x16x32_bf16 v[2:5], v[168:171], v[236:239], v[2:5]
	v_mfma_f32_16x16x32_bf16 v[6:9], v[160:163], v[236:239], v[6:9]
	v_mfma_f32_16x16x32_bf16 v[14:17], v[152:155], v[236:239], v[14:17]
	v_mfma_f32_16x16x32_bf16 v[22:25], v[140:143], v[236:239], v[22:25]
	s_setprio 0
	s_setprio 1
	v_mfma_f32_16x16x32_bf16 v[62:65], v[148:151], v[198:201], v[62:65]
	v_mfma_f32_16x16x32_bf16 v[58:61], v[156:159], v[198:201], v[58:61]
	v_mfma_f32_16x16x32_bf16 v[50:53], v[164:167], v[198:201], v[50:53]
	v_mfma_f32_16x16x32_bf16 v[42:45], v[190:193], v[198:201], v[42:45]
	v_mfma_f32_16x16x32_bf16 v[26:29], v[190:193], v[206:209], v[26:29]
	v_mfma_f32_16x16x32_bf16 v[34:37], v[164:167], v[206:209], v[34:37]
	v_mfma_f32_16x16x32_bf16 v[46:49], v[156:159], v[206:209], v[46:49]
	v_mfma_f32_16x16x32_bf16 v[54:57], v[148:151], v[206:209], v[54:57]
	v_mfma_f32_16x16x32_bf16 v[38:41], v[148:151], v[232:235], v[38:41]
	v_mfma_f32_16x16x32_bf16 v[30:33], v[156:159], v[232:235], v[30:33]
	v_mfma_f32_16x16x32_bf16 v[18:21], v[164:167], v[232:235], v[18:21]
	v_mfma_f32_16x16x32_bf16 v[10:13], v[190:193], v[232:235], v[10:13]
	v_mfma_f32_16x16x32_bf16 v[2:5], v[190:193], v[240:243], v[2:5]
	v_mfma_f32_16x16x32_bf16 v[6:9], v[164:167], v[240:243], v[6:9]
	v_mfma_f32_16x16x32_bf16 v[14:17], v[156:159], v[240:243], v[14:17]
	v_mfma_f32_16x16x32_bf16 v[22:25], v[148:151], v[240:243], v[22:25]
	s_setprio 0
	s_barrier
	s_add_i32 s49, 0, 0x18000
	s_add_i32 s50, 0, 0x1c000
	v_add_u32_e32 v156, s49, v145
	v_add_u32_e32 v175, s50, v145
	ds_read_b128 v[140:143], v156
	ds_read_b128 v[148:151], v156 offset:1024
	ds_read_b128 v[152:155], v156 offset:2048
	ds_read_b128 v[156:159], v156 offset:3072
	ds_read_b128 v[160:163], v175
	ds_read_b128 v[164:167], v175 offset:1024
	ds_read_b128 v[168:171], v175 offset:2048
	ds_read_b128 v[190:193], v175 offset:3072
	s_add_u32 s24, s24, 0x100000
	s_addc_u32 s25, s25, 0
	s_mov_b32 m0, s37
	v_lshl_add_u64 v[244:245], s[24:25], 0, v[134:135]
	ds_read_b128 v[194:197], v147 offset:32768
	ds_read_b128 v[198:201], v147 offset:33792
	ds_read_b128 v[202:205], v147 offset:34816
	ds_read_b128 v[206:209], v147 offset:35840
	ds_read_b128 v[228:231], v147 offset:36864
	ds_read_b128 v[232:235], v147 offset:37888
	ds_read_b128 v[236:239], v147 offset:38912
	ds_read_b128 v[240:243], v147 offset:39936
	global_load_lds_dwordx4 v[244:245], off
	v_lshl_add_u64 v[244:245], s[24:25], 0, v[132:133]
	s_mov_b32 m0, s38
	s_nop 0
	global_load_lds_dwordx4 v[244:245], off
	s_waitcnt vmcnt(8)
	s_waitcnt lgkmcnt(0)
	s_barrier
	s_setprio 1
	s_waitcnt lgkmcnt(0)
	v_mfma_f32_16x16x32_bf16 v[126:129], v[140:143], v[194:197], v[126:129]
	v_mfma_f32_16x16x32_bf16 v[122:125], v[152:155], v[194:197], v[122:125]
	v_mfma_f32_16x16x32_bf16 v[114:117], v[160:163], v[194:197], v[114:117]
	v_mfma_f32_16x16x32_bf16 v[106:109], v[168:171], v[194:197], v[106:109]
	v_mfma_f32_16x16x32_bf16 v[90:93], v[168:171], v[202:205], v[90:93]
	v_mfma_f32_16x16x32_bf16 v[98:101], v[160:163], v[202:205], v[98:101]
	v_mfma_f32_16x16x32_bf16 v[110:113], v[152:155], v[202:205], v[110:113]
	v_mfma_f32_16x16x32_bf16 v[118:121], v[140:143], v[202:205], v[118:121]
	v_mfma_f32_16x16x32_bf16 v[102:105], v[140:143], v[228:231], v[102:105]
	v_mfma_f32_16x16x32_bf16 v[94:97], v[152:155], v[228:231], v[94:97]
	v_mfma_f32_16x16x32_bf16 v[82:85], v[160:163], v[228:231], v[82:85]
	v_mfma_f32_16x16x32_bf16 v[74:77], v[168:171], v[228:231], v[74:77]
	v_mfma_f32_16x16x32_bf16 v[66:69], v[168:171], v[236:239], v[66:69]
	v_mfma_f32_16x16x32_bf16 v[70:73], v[160:163], v[236:239], v[70:73]
	v_mfma_f32_16x16x32_bf16 v[78:81], v[152:155], v[236:239], v[78:81]
	v_mfma_f32_16x16x32_bf16 v[86:89], v[140:143], v[236:239], v[86:89]
	s_setprio 0
	s_setprio 1
	v_mfma_f32_16x16x32_bf16 v[126:129], v[148:151], v[198:201], v[126:129]
	v_mfma_f32_16x16x32_bf16 v[122:125], v[156:159], v[198:201], v[122:125]
	v_mfma_f32_16x16x32_bf16 v[114:117], v[164:167], v[198:201], v[114:117]
	v_mfma_f32_16x16x32_bf16 v[106:109], v[190:193], v[198:201], v[106:109]
	v_mfma_f32_16x16x32_bf16 v[90:93], v[190:193], v[206:209], v[90:93]
	v_mfma_f32_16x16x32_bf16 v[98:101], v[164:167], v[206:209], v[98:101]
	v_mfma_f32_16x16x32_bf16 v[110:113], v[156:159], v[206:209], v[110:113]
	v_mfma_f32_16x16x32_bf16 v[118:121], v[148:151], v[206:209], v[118:121]
	v_mfma_f32_16x16x32_bf16 v[102:105], v[148:151], v[232:235], v[102:105]
	v_mfma_f32_16x16x32_bf16 v[94:97], v[156:159], v[232:235], v[94:97]
	v_mfma_f32_16x16x32_bf16 v[82:85], v[164:167], v[232:235], v[82:85]
	v_mfma_f32_16x16x32_bf16 v[74:77], v[190:193], v[232:235], v[74:77]
	v_mfma_f32_16x16x32_bf16 v[66:69], v[190:193], v[240:243], v[66:69]
	v_mfma_f32_16x16x32_bf16 v[70:73], v[164:167], v[240:243], v[70:73]
	v_mfma_f32_16x16x32_bf16 v[78:81], v[156:159], v[240:243], v[78:81]
	v_mfma_f32_16x16x32_bf16 v[86:89], v[148:151], v[240:243], v[86:89]
	s_setprio 0
	s_barrier
	s_add_i32 s24, s49, s26
	v_lshl_add_u64 v[172:173], v[172:173], 0, s[34:35]
	s_mov_b32 m0, s24
	ds_read_b128 v[194:197], v147 offset:49152
	ds_read_b128 v[198:201], v147 offset:50176
	ds_read_b128 v[202:205], v147 offset:51200
	ds_read_b128 v[206:209], v147 offset:52224
	ds_read_b128 v[228:231], v147 offset:53248
	ds_read_b128 v[232:235], v147 offset:54272
	ds_read_b128 v[236:239], v147 offset:55296
	ds_read_b128 v[240:243], v147 offset:56320
	global_load_lds_dwordx4 v[172:173], off
	s_add_i32 m0, s24, 0x2000
	s_add_u32 s22, s22, 0x100080
	v_lshl_add_u64 v[172:173], v[178:179], 0, s[34:35]
	s_addc_u32 s23, s23, 0
	s_add_i32 s24, s50, s26
	global_load_lds_dwordx4 v[172:173], off
	v_lshl_add_u64 v[172:173], s[22:23], 0, v[0:1]
	s_mov_b32 m0, s24
	s_nop 0
	global_load_lds_dwordx4 v[172:173], off
	v_lshl_add_u64 v[172:173], s[22:23], 0, v[130:131]
	s_add_i32 m0, s24, 0x2000
	s_nop 0
	global_load_lds_dwordx4 v[172:173], off
	v_lshl_add_u64 v[172:173], v[180:181], 0, s[34:35]
	s_mov_b32 m0, s39
	s_nop 0
	global_load_lds_dwordx4 v[172:173], off
	v_lshl_add_u64 v[172:173], v[210:211], 0, s[34:35]
	s_mov_b32 m0, s40
	s_nop 0
	global_load_lds_dwordx4 v[172:173], off
	s_waitcnt vmcnt(8)
	s_waitcnt lgkmcnt(0)
	s_barrier
	s_setprio 1
	s_waitcnt lgkmcnt(0)
	v_mfma_f32_16x16x32_bf16 v[62:65], v[140:143], v[194:197], v[62:65]
	v_mfma_f32_16x16x32_bf16 v[58:61], v[152:155], v[194:197], v[58:61]
	v_mfma_f32_16x16x32_bf16 v[50:53], v[160:163], v[194:197], v[50:53]
	v_mfma_f32_16x16x32_bf16 v[42:45], v[168:171], v[194:197], v[42:45]
	v_mfma_f32_16x16x32_bf16 v[26:29], v[168:171], v[202:205], v[26:29]
	v_mfma_f32_16x16x32_bf16 v[34:37], v[160:163], v[202:205], v[34:37]
	v_mfma_f32_16x16x32_bf16 v[46:49], v[152:155], v[202:205], v[46:49]
	v_mfma_f32_16x16x32_bf16 v[54:57], v[140:143], v[202:205], v[54:57]
	v_mfma_f32_16x16x32_bf16 v[38:41], v[140:143], v[228:231], v[38:41]
	v_mfma_f32_16x16x32_bf16 v[30:33], v[152:155], v[228:231], v[30:33]
	v_mfma_f32_16x16x32_bf16 v[18:21], v[160:163], v[228:231], v[18:21]
	v_mfma_f32_16x16x32_bf16 v[10:13], v[168:171], v[228:231], v[10:13]
	v_mfma_f32_16x16x32_bf16 v[2:5], v[168:171], v[236:239], v[2:5]
	v_mfma_f32_16x16x32_bf16 v[6:9], v[160:163], v[236:239], v[6:9]
	v_mfma_f32_16x16x32_bf16 v[14:17], v[152:155], v[236:239], v[14:17]
	v_mfma_f32_16x16x32_bf16 v[22:25], v[140:143], v[236:239], v[22:25]
	s_setprio 0
	s_setprio 1
	v_mfma_f32_16x16x32_bf16 v[62:65], v[148:151], v[198:201], v[62:65]
	v_mfma_f32_16x16x32_bf16 v[58:61], v[156:159], v[198:201], v[58:61]
	v_mfma_f32_16x16x32_bf16 v[50:53], v[164:167], v[198:201], v[50:53]
	v_mfma_f32_16x16x32_bf16 v[42:45], v[190:193], v[198:201], v[42:45]
	v_mfma_f32_16x16x32_bf16 v[26:29], v[190:193], v[206:209], v[26:29]
	v_mfma_f32_16x16x32_bf16 v[34:37], v[164:167], v[206:209], v[34:37]
	v_mfma_f32_16x16x32_bf16 v[46:49], v[156:159], v[206:209], v[46:49]
	v_mfma_f32_16x16x32_bf16 v[54:57], v[148:151], v[206:209], v[54:57]
	v_mfma_f32_16x16x32_bf16 v[38:41], v[148:151], v[232:235], v[38:41]
	v_mfma_f32_16x16x32_bf16 v[30:33], v[156:159], v[232:235], v[30:33]
	v_mfma_f32_16x16x32_bf16 v[18:21], v[164:167], v[232:235], v[18:21]
	v_mfma_f32_16x16x32_bf16 v[10:13], v[190:193], v[232:235], v[10:13]
	v_mfma_f32_16x16x32_bf16 v[2:5], v[190:193], v[240:243], v[2:5]
	v_mfma_f32_16x16x32_bf16 v[6:9], v[164:167], v[240:243], v[6:9]
	v_mfma_f32_16x16x32_bf16 v[14:17], v[156:159], v[240:243], v[14:17]
	v_mfma_f32_16x16x32_bf16 v[22:25], v[148:151], v[240:243], v[22:25]
	s_setprio 0
	s_barrier
	s_add_i32 s48, s48, 2
	s_add_u32 s18, s18, 0x100
	s_addc_u32 s19, s19, 0
	s_add_u32 s46, s46, 0x100
	s_addc_u32 s47, s47, 0
	s_cmp_gt_u32 s48, 61
	s_cbranch_scc0 .LBB0_139
	s_and_b64 vcc, exec, s[4:5]
	s_cbranch_vccz .LBB0_142
	s_barrier

.LBB0_575:
	s_add_u32 s22, s18, 0xfff00080
	s_addc_u32 s23, s19, -1
	s_add_i32 s53, 0, 0x10000
	s_cmp_eq_u32 s52, 60
	s_cselect_b32 s25, s9, s23
	s_cselect_b32 s24, s48, s22
	v_add_u32_e32 v140, s53, v143
	s_cselect_b32 s23, s7, s51
	s_cselect_b32 s22, s49, s50
	s_add_i32 s56, 0, 0x14000
	ds_read_b128 v[146:149], v140
	ds_read_b128 v[150:153], v140 offset:1024
	ds_read_b128 v[154:157], v140 offset:2048
	ds_read_b128 v[158:161], v140 offset:3072
	v_add_u32_e32 v140, s56, v143
	ds_read_b128 v[162:165], v140
	ds_read_b128 v[166:169], v140 offset:1024
	ds_read_b128 v[170:173], v140 offset:2048
	ds_read_b128 v[178:181], v140 offset:3072
	v_lshl_add_u64 v[140:141], s[18:19], 0, v[136:137]
	s_add_i32 m0, s39, 0xc000
	ds_read_b128 v[190:193], v145
	ds_read_b128 v[194:197], v145 offset:1024
	ds_read_b128 v[198:201], v145 offset:2048
	ds_read_b128 v[202:205], v145 offset:3072
	ds_read_b128 v[206:209], v145 offset:4096
	ds_read_b128 v[228:231], v145 offset:5120
	ds_read_b128 v[232:235], v145 offset:6144
	ds_read_b128 v[236:239], v145 offset:7168
	global_load_lds_dwordx4 v[140:141], off
	v_lshl_add_u64 v[140:141], s[18:19], 0, v[138:139]
	s_add_i32 m0, s39, 0xe000
	s_nop 0
	global_load_lds_dwordx4 v[140:141], off
	s_waitcnt vmcnt(8)
	s_waitcnt lgkmcnt(0)
	s_barrier
	s_setprio 1
	s_waitcnt lgkmcnt(0)
	v_mfma_f32_16x16x32_bf16 v[126:129], v[146:149], v[190:193], v[126:129]
	v_mfma_f32_16x16x32_bf16 v[122:125], v[154:157], v[190:193], v[122:125]
	v_mfma_f32_16x16x32_bf16 v[114:117], v[162:165], v[190:193], v[114:117]
	v_mfma_f32_16x16x32_bf16 v[106:109], v[170:173], v[190:193], v[106:109]
	v_mfma_f32_16x16x32_bf16 v[90:93], v[170:173], v[198:201], v[90:93]
	v_mfma_f32_16x16x32_bf16 v[98:101], v[162:165], v[198:201], v[98:101]
	v_mfma_f32_16x16x32_bf16 v[110:113], v[154:157], v[198:201], v[110:113]
	v_mfma_f32_16x16x32_bf16 v[118:121], v[146:149], v[198:201], v[118:121]
	v_mfma_f32_16x16x32_bf16 v[102:105], v[146:149], v[206:209], v[102:105]
	v_mfma_f32_16x16x32_bf16 v[94:97], v[154:157], v[206:209], v[94:97]
	v_mfma_f32_16x16x32_bf16 v[82:85], v[162:165], v[206:209], v[82:85]
	v_mfma_f32_16x16x32_bf16 v[74:77], v[170:173], v[206:209], v[74:77]
	v_mfma_f32_16x16x32_bf16 v[66:69], v[170:173], v[232:235], v[66:69]
	v_mfma_f32_16x16x32_bf16 v[70:73], v[162:165], v[232:235], v[70:73]
	v_mfma_f32_16x16x32_bf16 v[78:81], v[154:157], v[232:235], v[78:81]
	v_mfma_f32_16x16x32_bf16 v[86:89], v[146:149], v[232:235], v[86:89]
	s_setprio 0
	s_setprio 1
	v_mfma_f32_16x16x32_bf16 v[126:129], v[150:153], v[194:197], v[126:129]
	v_mfma_f32_16x16x32_bf16 v[122:125], v[158:161], v[194:197], v[122:125]
	v_mfma_f32_16x16x32_bf16 v[114:117], v[166:169], v[194:197], v[114:117]
	v_mfma_f32_16x16x32_bf16 v[106:109], v[178:181], v[194:197], v[106:109]
	v_mfma_f32_16x16x32_bf16 v[90:93], v[178:181], v[202:205], v[90:93]
	v_mfma_f32_16x16x32_bf16 v[98:101], v[166:169], v[202:205], v[98:101]
	v_mfma_f32_16x16x32_bf16 v[110:113], v[158:161], v[202:205], v[110:113]
	v_mfma_f32_16x16x32_bf16 v[118:121], v[150:153], v[202:205], v[118:121]
	v_mfma_f32_16x16x32_bf16 v[102:105], v[150:153], v[228:231], v[102:105]
	v_mfma_f32_16x16x32_bf16 v[94:97], v[158:161], v[228:231], v[94:97]
	v_mfma_f32_16x16x32_bf16 v[82:85], v[166:169], v[228:231], v[82:85]
	v_mfma_f32_16x16x32_bf16 v[74:77], v[178:181], v[228:231], v[74:77]
	v_mfma_f32_16x16x32_bf16 v[66:69], v[178:181], v[236:239], v[66:69]
	v_mfma_f32_16x16x32_bf16 v[70:73], v[166:169], v[236:239], v[70:73]
	v_mfma_f32_16x16x32_bf16 v[78:81], v[158:161], v[236:239], v[78:81]
	v_mfma_f32_16x16x32_bf16 v[86:89], v[150:153], v[236:239], v[86:89]
	s_setprio 0
	s_barrier
	s_add_i32 s53, s53, s38
	v_lshl_add_u64 v[140:141], s[22:23], 0, v[0:1]
	s_mov_b32 m0, s53
	ds_read_b128 v[190:193], v145 offset:16384
	ds_read_b128 v[194:197], v145 offset:17408
	ds_read_b128 v[198:201], v145 offset:18432
	ds_read_b128 v[202:205], v145 offset:19456
	ds_read_b128 v[206:209], v145 offset:20480
	ds_read_b128 v[228:231], v145 offset:21504
	ds_read_b128 v[232:235], v145 offset:22528
	ds_read_b128 v[236:239], v145 offset:23552
	global_load_lds_dwordx4 v[140:141], off
	s_add_i32 m0, s53, 0x2000
	s_add_u32 s54, s22, 0x100000
	v_lshl_add_u64 v[186:187], s[22:23], 0, v[130:131]
	s_addc_u32 s55, s23, 0
	s_add_i32 s53, s56, s38
	global_load_lds_dwordx4 v[186:187], off
	v_lshl_add_u64 v[188:189], s[54:55], 0, v[0:1]
	s_mov_b32 m0, s53
	v_lshl_add_u64 v[210:211], s[24:25], 0, v[132:133]
	global_load_lds_dwordx4 v[188:189], off
	v_lshl_add_u64 v[188:189], s[54:55], 0, v[130:131]
	s_add_i32 m0, s53, 0x2000
	s_nop 0
	global_load_lds_dwordx4 v[188:189], off
	v_lshl_add_u64 v[188:189], s[24:25], 0, v[134:135]
	s_mov_b32 m0, s39
	s_nop 0
	global_load_lds_dwordx4 v[188:189], off
	s_mov_b32 m0, s40
	s_nop 0
	global_load_lds_dwordx4 v[210:211], off
	s_waitcnt vmcnt(8)
	s_waitcnt lgkmcnt(0)
	s_barrier
	s_setprio 1
	s_waitcnt lgkmcnt(0)
	v_mfma_f32_16x16x32_bf16 v[62:65], v[146:149], v[190:193], v[62:65]
	v_mfma_f32_16x16x32_bf16 v[58:61], v[154:157], v[190:193], v[58:61]
	v_mfma_f32_16x16x32_bf16 v[50:53], v[162:165], v[190:193], v[50:53]
	v_mfma_f32_16x16x32_bf16 v[42:45], v[170:173], v[190:193], v[42:45]
	v_mfma_f32_16x16x32_bf16 v[26:29], v[170:173], v[198:201], v[26:29]
	v_mfma_f32_16x16x32_bf16 v[34:37], v[162:165], v[198:201], v[34:37]
	v_mfma_f32_16x16x32_bf16 v[46:49], v[154:157], v[198:201], v[46:49]
	v_mfma_f32_16x16x32_bf16 v[54:57], v[146:149], v[198:201], v[54:57]
	v_mfma_f32_16x16x32_bf16 v[38:41], v[146:149], v[206:209], v[38:41]
	v_mfma_f32_16x16x32_bf16 v[30:33], v[154:157], v[206:209], v[30:33]
	v_mfma_f32_16x16x32_bf16 v[18:21], v[162:165], v[206:209], v[18:21]
	v_mfma_f32_16x16x32_bf16 v[10:13], v[170:173], v[206:209], v[10:13]
	v_mfma_f32_16x16x32_bf16 v[2:5], v[170:173], v[232:235], v[2:5]
	v_mfma_f32_16x16x32_bf16 v[6:9], v[162:165], v[232:235], v[6:9]
	v_mfma_f32_16x16x32_bf16 v[14:17], v[154:157], v[232:235], v[14:17]
	v_mfma_f32_16x16x32_bf16 v[22:25], v[146:149], v[232:235], v[22:25]
	s_setprio 0
	s_setprio 1
	v_mfma_f32_16x16x32_bf16 v[62:65], v[150:153], v[194:197], v[62:65]
	v_mfma_f32_16x16x32_bf16 v[58:61], v[158:161], v[194:197], v[58:61]
	v_mfma_f32_16x16x32_bf16 v[50:53], v[166:169], v[194:197], v[50:53]
	v_mfma_f32_16x16x32_bf16 v[42:45], v[178:181], v[194:197], v[42:45]
	v_mfma_f32_16x16x32_bf16 v[26:29], v[178:181], v[202:205], v[26:29]
	v_mfma_f32_16x16x32_bf16 v[34:37], v[166:169], v[202:205], v[34:37]
	v_mfma_f32_16x16x32_bf16 v[46:49], v[158:161], v[202:205], v[46:49]
	v_mfma_f32_16x16x32_bf16 v[54:57], v[150:153], v[202:205], v[54:57]
	v_mfma_f32_16x16x32_bf16 v[38:41], v[150:153], v[228:231], v[38:41]
	v_mfma_f32_16x16x32_bf16 v[30:33], v[158:161], v[228:231], v[30:33]
	v_mfma_f32_16x16x32_bf16 v[18:21], v[166:169], v[228:231], v[18:21]
	v_mfma_f32_16x16x32_bf16 v[10:13], v[178:181], v[228:231], v[10:13]
	v_mfma_f32_16x16x32_bf16 v[2:5], v[178:181], v[236:239], v[2:5]
	v_mfma_f32_16x16x32_bf16 v[6:9], v[166:169], v[236:239], v[6:9]
	v_mfma_f32_16x16x32_bf16 v[14:17], v[158:161], v[236:239], v[14:17]
	v_mfma_f32_16x16x32_bf16 v[22:25], v[150:153], v[236:239], v[22:25]
	s_setprio 0
	s_barrier
	s_add_i32 s53, 0, 0x18000
	s_add_i32 s54, 0, 0x1c000
	v_add_u32_e32 v158, s53, v143
	v_add_u32_e32 v175, s54, v143
	ds_read_b128 v[146:149], v158
	ds_read_b128 v[150:153], v158 offset:1024
	ds_read_b128 v[154:157], v158 offset:2048
	ds_read_b128 v[158:161], v158 offset:3072
	ds_read_b128 v[162:165], v175
	ds_read_b128 v[166:169], v175 offset:1024
	ds_read_b128 v[170:173], v175 offset:2048
	ds_read_b128 v[178:181], v175 offset:3072
	s_add_u32 s24, s24, 0x100000
	s_addc_u32 s25, s25, 0
	s_mov_b32 m0, s41
	v_lshl_add_u64 v[226:227], s[24:25], 0, v[134:135]
	ds_read_b128 v[190:193], v145 offset:32768
	ds_read_b128 v[194:197], v145 offset:33792
	ds_read_b128 v[198:201], v145 offset:34816
	ds_read_b128 v[202:205], v145 offset:35840
	ds_read_b128 v[206:209], v145 offset:36864
	ds_read_b128 v[228:231], v145 offset:37888
	ds_read_b128 v[232:235], v145 offset:38912
	ds_read_b128 v[236:239], v145 offset:39936
	global_load_lds_dwordx4 v[226:227], off
	v_lshl_add_u64 v[226:227], s[24:25], 0, v[132:133]
	s_mov_b32 m0, s42
	s_nop 0
	global_load_lds_dwordx4 v[226:227], off
	s_waitcnt vmcnt(8)
	s_waitcnt lgkmcnt(0)
	s_barrier
	s_setprio 1
	s_waitcnt lgkmcnt(0)
	v_mfma_f32_16x16x32_bf16 v[126:129], v[146:149], v[190:193], v[126:129]
	v_mfma_f32_16x16x32_bf16 v[122:125], v[154:157], v[190:193], v[122:125]
	v_mfma_f32_16x16x32_bf16 v[114:117], v[162:165], v[190:193], v[114:117]
	v_mfma_f32_16x16x32_bf16 v[106:109], v[170:173], v[190:193], v[106:109]
	v_mfma_f32_16x16x32_bf16 v[90:93], v[170:173], v[198:201], v[90:93]
	v_mfma_f32_16x16x32_bf16 v[98:101], v[162:165], v[198:201], v[98:101]
	v_mfma_f32_16x16x32_bf16 v[110:113], v[154:157], v[198:201], v[110:113]
	v_mfma_f32_16x16x32_bf16 v[118:121], v[146:149], v[198:201], v[118:121]
	v_mfma_f32_16x16x32_bf16 v[102:105], v[146:149], v[206:209], v[102:105]
	v_mfma_f32_16x16x32_bf16 v[94:97], v[154:157], v[206:209], v[94:97]
	v_mfma_f32_16x16x32_bf16 v[82:85], v[162:165], v[206:209], v[82:85]
	v_mfma_f32_16x16x32_bf16 v[74:77], v[170:173], v[206:209], v[74:77]
	v_mfma_f32_16x16x32_bf16 v[66:69], v[170:173], v[232:235], v[66:69]
	v_mfma_f32_16x16x32_bf16 v[70:73], v[162:165], v[232:235], v[70:73]
	v_mfma_f32_16x16x32_bf16 v[78:81], v[154:157], v[232:235], v[78:81]
	v_mfma_f32_16x16x32_bf16 v[86:89], v[146:149], v[232:235], v[86:89]
	s_setprio 0
	s_setprio 1
	v_mfma_f32_16x16x32_bf16 v[126:129], v[150:153], v[194:197], v[126:129]
	v_mfma_f32_16x16x32_bf16 v[122:125], v[158:161], v[194:197], v[122:125]
	v_mfma_f32_16x16x32_bf16 v[114:117], v[166:169], v[194:197], v[114:117]
	v_mfma_f32_16x16x32_bf16 v[106:109], v[178:181], v[194:197], v[106:109]
	v_mfma_f32_16x16x32_bf16 v[90:93], v[178:181], v[202:205], v[90:93]
	v_mfma_f32_16x16x32_bf16 v[98:101], v[166:169], v[202:205], v[98:101]
	v_mfma_f32_16x16x32_bf16 v[110:113], v[158:161], v[202:205], v[110:113]
	v_mfma_f32_16x16x32_bf16 v[118:121], v[150:153], v[202:205], v[118:121]
	v_mfma_f32_16x16x32_bf16 v[102:105], v[150:153], v[228:231], v[102:105]
	v_mfma_f32_16x16x32_bf16 v[94:97], v[158:161], v[228:231], v[94:97]
	v_mfma_f32_16x16x32_bf16 v[82:85], v[166:169], v[228:231], v[82:85]
	v_mfma_f32_16x16x32_bf16 v[74:77], v[178:181], v[228:231], v[74:77]
	v_mfma_f32_16x16x32_bf16 v[66:69], v[178:181], v[236:239], v[66:69]
	v_mfma_f32_16x16x32_bf16 v[70:73], v[166:169], v[236:239], v[70:73]
	v_mfma_f32_16x16x32_bf16 v[78:81], v[158:161], v[236:239], v[78:81]
	v_mfma_f32_16x16x32_bf16 v[86:89], v[150:153], v[236:239], v[86:89]
	s_setprio 0
	s_barrier
	s_add_i32 s24, s53, s38
	v_lshl_add_u64 v[140:141], v[140:141], 0, s[34:35]
	s_mov_b32 m0, s24
	ds_read_b128 v[190:193], v145 offset:49152
	ds_read_b128 v[194:197], v145 offset:50176
	ds_read_b128 v[198:201], v145 offset:51200
	ds_read_b128 v[202:205], v145 offset:52224
	ds_read_b128 v[206:209], v145 offset:53248
	ds_read_b128 v[228:231], v145 offset:54272
	ds_read_b128 v[232:235], v145 offset:55296
	ds_read_b128 v[236:239], v145 offset:56320
	global_load_lds_dwordx4 v[140:141], off
	s_add_i32 m0, s24, 0x2000
	s_add_u32 s22, s22, 0x100080
	v_lshl_add_u64 v[140:141], v[186:187], 0, s[34:35]
	s_addc_u32 s23, s23, 0
	s_add_i32 s24, s54, s38
	global_load_lds_dwordx4 v[140:141], off
	v_lshl_add_u64 v[140:141], s[22:23], 0, v[0:1]
	s_mov_b32 m0, s24
	s_nop 0
	global_load_lds_dwordx4 v[140:141], off
	v_lshl_add_u64 v[140:141], s[22:23], 0, v[130:131]
	s_add_i32 m0, s24, 0x2000
	s_nop 0
	global_load_lds_dwordx4 v[140:141], off
	v_lshl_add_u64 v[140:141], v[188:189], 0, s[34:35]
	s_mov_b32 m0, s43
	s_nop 0
	global_load_lds_dwordx4 v[140:141], off
	v_lshl_add_u64 v[140:141], v[210:211], 0, s[34:35]
	s_mov_b32 m0, s44
	s_nop 0
	global_load_lds_dwordx4 v[140:141], off
	s_waitcnt vmcnt(8)
	s_waitcnt lgkmcnt(0)
	s_barrier
	s_setprio 1
	s_waitcnt lgkmcnt(0)
	v_mfma_f32_16x16x32_bf16 v[62:65], v[146:149], v[190:193], v[62:65]
	v_mfma_f32_16x16x32_bf16 v[58:61], v[154:157], v[190:193], v[58:61]
	v_mfma_f32_16x16x32_bf16 v[50:53], v[162:165], v[190:193], v[50:53]
	v_mfma_f32_16x16x32_bf16 v[42:45], v[170:173], v[190:193], v[42:45]
	v_mfma_f32_16x16x32_bf16 v[26:29], v[170:173], v[198:201], v[26:29]
	v_mfma_f32_16x16x32_bf16 v[34:37], v[162:165], v[198:201], v[34:37]
	v_mfma_f32_16x16x32_bf16 v[46:49], v[154:157], v[198:201], v[46:49]
	v_mfma_f32_16x16x32_bf16 v[54:57], v[146:149], v[198:201], v[54:57]
	v_mfma_f32_16x16x32_bf16 v[38:41], v[146:149], v[206:209], v[38:41]
	v_mfma_f32_16x16x32_bf16 v[30:33], v[154:157], v[206:209], v[30:33]
	v_mfma_f32_16x16x32_bf16 v[18:21], v[162:165], v[206:209], v[18:21]
	v_mfma_f32_16x16x32_bf16 v[10:13], v[170:173], v[206:209], v[10:13]
	v_mfma_f32_16x16x32_bf16 v[2:5], v[170:173], v[232:235], v[2:5]
	v_mfma_f32_16x16x32_bf16 v[6:9], v[162:165], v[232:235], v[6:9]
	v_mfma_f32_16x16x32_bf16 v[14:17], v[154:157], v[232:235], v[14:17]
	v_mfma_f32_16x16x32_bf16 v[22:25], v[146:149], v[232:235], v[22:25]
	s_setprio 0
	s_setprio 1
	v_mfma_f32_16x16x32_bf16 v[62:65], v[150:153], v[194:197], v[62:65]
	v_mfma_f32_16x16x32_bf16 v[58:61], v[158:161], v[194:197], v[58:61]
	v_mfma_f32_16x16x32_bf16 v[50:53], v[166:169], v[194:197], v[50:53]
	v_mfma_f32_16x16x32_bf16 v[42:45], v[178:181], v[194:197], v[42:45]
	v_mfma_f32_16x16x32_bf16 v[26:29], v[178:181], v[202:205], v[26:29]
	v_mfma_f32_16x16x32_bf16 v[34:37], v[166:169], v[202:205], v[34:37]
	v_mfma_f32_16x16x32_bf16 v[46:49], v[158:161], v[202:205], v[46:49]
	v_mfma_f32_16x16x32_bf16 v[54:57], v[150:153], v[202:205], v[54:57]
	v_mfma_f32_16x16x32_bf16 v[38:41], v[150:153], v[228:231], v[38:41]
	v_mfma_f32_16x16x32_bf16 v[30:33], v[158:161], v[228:231], v[30:33]
	v_mfma_f32_16x16x32_bf16 v[18:21], v[166:169], v[228:231], v[18:21]
	v_mfma_f32_16x16x32_bf16 v[10:13], v[178:181], v[228:231], v[10:13]
	v_mfma_f32_16x16x32_bf16 v[2:5], v[178:181], v[236:239], v[2:5]
	v_mfma_f32_16x16x32_bf16 v[6:9], v[166:169], v[236:239], v[6:9]
	v_mfma_f32_16x16x32_bf16 v[14:17], v[158:161], v[236:239], v[14:17]
	v_mfma_f32_16x16x32_bf16 v[22:25], v[150:153], v[236:239], v[22:25]
	s_setprio 0
	s_barrier
	s_add_i32 s52, s52, 2
	s_add_u32 s18, s18, 0x100
	s_addc_u32 s19, s19, 0
	s_add_u32 s50, s50, 0x100
	s_addc_u32 s51, s51, 0
	s_cmp_gt_u32 s52, 61
	s_cbranch_scc0 .LBB0_575
	s_and_b64 vcc, exec, s[4:5]
	s_cbranch_vccz .LBB0_578
	s_barrier

.LBB0_721:
	s_add_u32 s18, s16, 0xfff00080
	s_addc_u32 s19, s17, -1
	s_add_i32 s53, 0, 0x10000
	s_cmp_eq_u32 s52, 60
	s_cselect_b32 s23, s7, s19
	s_cselect_b32 s22, s48, s18
	v_add_u32_e32 v140, s53, v143
	s_cselect_b32 s19, s5, s51
	s_cselect_b32 s18, s49, s50
	s_add_i32 s56, 0, 0x14000
	ds_read_b128 v[146:149], v140
	ds_read_b128 v[150:153], v140 offset:1024
	ds_read_b128 v[154:157], v140 offset:2048
	ds_read_b128 v[158:161], v140 offset:3072
	v_add_u32_e32 v140, s56, v143
	ds_read_b128 v[162:165], v140
	ds_read_b128 v[166:169], v140 offset:1024
	ds_read_b128 v[170:173], v140 offset:2048
	ds_read_b128 v[178:181], v140 offset:3072
	v_lshl_add_u64 v[140:141], s[16:17], 0, v[136:137]
	s_add_i32 m0, s31, 0xc000
	ds_read_b128 v[190:193], v145
	ds_read_b128 v[194:197], v145 offset:1024
	ds_read_b128 v[198:201], v145 offset:2048
	ds_read_b128 v[202:205], v145 offset:3072
	ds_read_b128 v[206:209], v145 offset:4096
	ds_read_b128 v[228:231], v145 offset:5120
	ds_read_b128 v[232:235], v145 offset:6144
	ds_read_b128 v[236:239], v145 offset:7168
	global_load_lds_dwordx4 v[140:141], off
	v_lshl_add_u64 v[140:141], s[16:17], 0, v[138:139]
	s_add_i32 m0, s31, 0xe000
	s_nop 0
	global_load_lds_dwordx4 v[140:141], off
	s_waitcnt vmcnt(8)
	s_waitcnt lgkmcnt(0)
	s_barrier
	s_setprio 1
	s_waitcnt lgkmcnt(0)
	v_mfma_f32_16x16x32_bf16 v[126:129], v[146:149], v[190:193], v[126:129]
	v_mfma_f32_16x16x32_bf16 v[118:121], v[154:157], v[190:193], v[118:121]
	v_mfma_f32_16x16x32_bf16 v[122:125], v[162:165], v[190:193], v[122:125]
	v_mfma_f32_16x16x32_bf16 v[114:117], v[170:173], v[190:193], v[114:117]
	v_mfma_f32_16x16x32_bf16 v[98:101], v[170:173], v[198:201], v[98:101]
	v_mfma_f32_16x16x32_bf16 v[106:109], v[162:165], v[198:201], v[106:109]
	v_mfma_f32_16x16x32_bf16 v[102:105], v[154:157], v[198:201], v[102:105]
	v_mfma_f32_16x16x32_bf16 v[110:113], v[146:149], v[198:201], v[110:113]
	v_mfma_f32_16x16x32_bf16 v[94:97], v[146:149], v[206:209], v[94:97]
	v_mfma_f32_16x16x32_bf16 v[86:89], v[154:157], v[206:209], v[86:89]
	v_mfma_f32_16x16x32_bf16 v[90:93], v[162:165], v[206:209], v[90:93]
	v_mfma_f32_16x16x32_bf16 v[82:85], v[170:173], v[206:209], v[82:85]
	v_mfma_f32_16x16x32_bf16 v[66:69], v[170:173], v[232:235], v[66:69]
	v_mfma_f32_16x16x32_bf16 v[74:77], v[162:165], v[232:235], v[74:77]
	v_mfma_f32_16x16x32_bf16 v[70:73], v[154:157], v[232:235], v[70:73]
	v_mfma_f32_16x16x32_bf16 v[78:81], v[146:149], v[232:235], v[78:81]
	s_setprio 0
	s_setprio 1
	v_mfma_f32_16x16x32_bf16 v[126:129], v[150:153], v[194:197], v[126:129]
	v_mfma_f32_16x16x32_bf16 v[118:121], v[158:161], v[194:197], v[118:121]
	v_mfma_f32_16x16x32_bf16 v[122:125], v[166:169], v[194:197], v[122:125]
	v_mfma_f32_16x16x32_bf16 v[114:117], v[178:181], v[194:197], v[114:117]
	v_mfma_f32_16x16x32_bf16 v[98:101], v[178:181], v[202:205], v[98:101]
	v_mfma_f32_16x16x32_bf16 v[106:109], v[166:169], v[202:205], v[106:109]
	v_mfma_f32_16x16x32_bf16 v[102:105], v[158:161], v[202:205], v[102:105]
	v_mfma_f32_16x16x32_bf16 v[110:113], v[150:153], v[202:205], v[110:113]
	v_mfma_f32_16x16x32_bf16 v[94:97], v[150:153], v[228:231], v[94:97]
	v_mfma_f32_16x16x32_bf16 v[86:89], v[158:161], v[228:231], v[86:89]
	v_mfma_f32_16x16x32_bf16 v[90:93], v[166:169], v[228:231], v[90:93]
	v_mfma_f32_16x16x32_bf16 v[82:85], v[178:181], v[228:231], v[82:85]
	v_mfma_f32_16x16x32_bf16 v[66:69], v[178:181], v[236:239], v[66:69]
	v_mfma_f32_16x16x32_bf16 v[74:77], v[166:169], v[236:239], v[74:77]
	v_mfma_f32_16x16x32_bf16 v[70:73], v[158:161], v[236:239], v[70:73]
	v_mfma_f32_16x16x32_bf16 v[78:81], v[150:153], v[236:239], v[78:81]
	s_setprio 0
	s_barrier
	s_add_i32 s53, s53, s26
	v_lshl_add_u64 v[140:141], s[18:19], 0, v[0:1]
	s_mov_b32 m0, s53
	ds_read_b128 v[190:193], v145 offset:16384
	ds_read_b128 v[194:197], v145 offset:17408
	ds_read_b128 v[198:201], v145 offset:18432
	ds_read_b128 v[202:205], v145 offset:19456
	ds_read_b128 v[206:209], v145 offset:20480
	ds_read_b128 v[228:231], v145 offset:21504
	ds_read_b128 v[232:235], v145 offset:22528
	ds_read_b128 v[236:239], v145 offset:23552
	global_load_lds_dwordx4 v[140:141], off
	s_add_i32 m0, s53, 0x2000
	s_add_u32 s54, s18, 0x100000
	v_lshl_add_u64 v[186:187], s[18:19], 0, v[130:131]
	s_addc_u32 s55, s19, 0
	s_add_i32 s53, s56, s26
	global_load_lds_dwordx4 v[186:187], off
	v_lshl_add_u64 v[188:189], s[54:55], 0, v[0:1]
	s_mov_b32 m0, s53
	v_lshl_add_u64 v[210:211], s[22:23], 0, v[132:133]
	global_load_lds_dwordx4 v[188:189], off
	v_lshl_add_u64 v[188:189], s[54:55], 0, v[130:131]
	s_add_i32 m0, s53, 0x2000
	s_nop 0
	global_load_lds_dwordx4 v[188:189], off
	v_lshl_add_u64 v[188:189], s[22:23], 0, v[134:135]
	s_mov_b32 m0, s31
	s_nop 0
	global_load_lds_dwordx4 v[188:189], off
	s_mov_b32 m0, s40
	s_nop 0
	global_load_lds_dwordx4 v[210:211], off
	s_waitcnt vmcnt(8)
	s_waitcnt lgkmcnt(0)
	s_barrier
	s_setprio 1
	s_waitcnt lgkmcnt(0)
	v_mfma_f32_16x16x32_bf16 v[62:65], v[146:149], v[190:193], v[62:65]
	v_mfma_f32_16x16x32_bf16 v[54:57], v[154:157], v[190:193], v[54:57]
	v_mfma_f32_16x16x32_bf16 v[58:61], v[162:165], v[190:193], v[58:61]
	v_mfma_f32_16x16x32_bf16 v[50:53], v[170:173], v[190:193], v[50:53]
	v_mfma_f32_16x16x32_bf16 v[34:37], v[170:173], v[198:201], v[34:37]
	v_mfma_f32_16x16x32_bf16 v[42:45], v[162:165], v[198:201], v[42:45]
	v_mfma_f32_16x16x32_bf16 v[38:41], v[154:157], v[198:201], v[38:41]
	v_mfma_f32_16x16x32_bf16 v[46:49], v[146:149], v[198:201], v[46:49]
	v_mfma_f32_16x16x32_bf16 v[30:33], v[146:149], v[206:209], v[30:33]
	v_mfma_f32_16x16x32_bf16 v[22:25], v[154:157], v[206:209], v[22:25]
	v_mfma_f32_16x16x32_bf16 v[26:29], v[162:165], v[206:209], v[26:29]
	v_mfma_f32_16x16x32_bf16 v[18:21], v[170:173], v[206:209], v[18:21]
	v_mfma_f32_16x16x32_bf16 v[2:5], v[170:173], v[232:235], v[2:5]
	v_mfma_f32_16x16x32_bf16 v[10:13], v[162:165], v[232:235], v[10:13]
	v_mfma_f32_16x16x32_bf16 v[6:9], v[154:157], v[232:235], v[6:9]
	v_mfma_f32_16x16x32_bf16 v[14:17], v[146:149], v[232:235], v[14:17]
	s_setprio 0
	s_setprio 1
	v_mfma_f32_16x16x32_bf16 v[62:65], v[150:153], v[194:197], v[62:65]
	v_mfma_f32_16x16x32_bf16 v[54:57], v[158:161], v[194:197], v[54:57]
	v_mfma_f32_16x16x32_bf16 v[58:61], v[166:169], v[194:197], v[58:61]
	v_mfma_f32_16x16x32_bf16 v[50:53], v[178:181], v[194:197], v[50:53]
	v_mfma_f32_16x16x32_bf16 v[34:37], v[178:181], v[202:205], v[34:37]
	v_mfma_f32_16x16x32_bf16 v[42:45], v[166:169], v[202:205], v[42:45]
	v_mfma_f32_16x16x32_bf16 v[38:41], v[158:161], v[202:205], v[38:41]
	v_mfma_f32_16x16x32_bf16 v[46:49], v[150:153], v[202:205], v[46:49]
	v_mfma_f32_16x16x32_bf16 v[30:33], v[150:153], v[228:231], v[30:33]
	v_mfma_f32_16x16x32_bf16 v[22:25], v[158:161], v[228:231], v[22:25]
	v_mfma_f32_16x16x32_bf16 v[26:29], v[166:169], v[228:231], v[26:29]
	v_mfma_f32_16x16x32_bf16 v[18:21], v[178:181], v[228:231], v[18:21]
	v_mfma_f32_16x16x32_bf16 v[2:5], v[178:181], v[236:239], v[2:5]
	v_mfma_f32_16x16x32_bf16 v[10:13], v[166:169], v[236:239], v[10:13]
	v_mfma_f32_16x16x32_bf16 v[6:9], v[158:161], v[236:239], v[6:9]
	v_mfma_f32_16x16x32_bf16 v[14:17], v[150:153], v[236:239], v[14:17]
	s_setprio 0
	s_barrier
	s_add_i32 s53, 0, 0x18000
	s_add_i32 s54, 0, 0x1c000
	v_add_u32_e32 v158, s53, v143
	v_add_u32_e32 v175, s54, v143
	ds_read_b128 v[146:149], v158
	ds_read_b128 v[150:153], v158 offset:1024
	ds_read_b128 v[154:157], v158 offset:2048
	ds_read_b128 v[158:161], v158 offset:3072
	ds_read_b128 v[162:165], v175
	ds_read_b128 v[166:169], v175 offset:1024
	ds_read_b128 v[170:173], v175 offset:2048
	ds_read_b128 v[178:181], v175 offset:3072
	s_add_u32 s22, s22, 0x100000
	s_addc_u32 s23, s23, 0
	s_mov_b32 m0, s41
	v_lshl_add_u64 v[226:227], s[22:23], 0, v[134:135]
	ds_read_b128 v[190:193], v145 offset:32768
	ds_read_b128 v[194:197], v145 offset:33792
	ds_read_b128 v[198:201], v145 offset:34816
	ds_read_b128 v[202:205], v145 offset:35840
	ds_read_b128 v[206:209], v145 offset:36864
	ds_read_b128 v[228:231], v145 offset:37888
	ds_read_b128 v[232:235], v145 offset:38912
	ds_read_b128 v[236:239], v145 offset:39936
	global_load_lds_dwordx4 v[226:227], off
	v_lshl_add_u64 v[226:227], s[22:23], 0, v[132:133]
	s_mov_b32 m0, s42
	s_nop 0
	global_load_lds_dwordx4 v[226:227], off
	s_waitcnt vmcnt(8)
	s_waitcnt lgkmcnt(0)
	s_barrier
	s_setprio 1
	s_waitcnt lgkmcnt(0)
	v_mfma_f32_16x16x32_bf16 v[126:129], v[146:149], v[190:193], v[126:129]
	v_mfma_f32_16x16x32_bf16 v[118:121], v[154:157], v[190:193], v[118:121]
	v_mfma_f32_16x16x32_bf16 v[122:125], v[162:165], v[190:193], v[122:125]
	v_mfma_f32_16x16x32_bf16 v[114:117], v[170:173], v[190:193], v[114:117]
	v_mfma_f32_16x16x32_bf16 v[98:101], v[170:173], v[198:201], v[98:101]
	v_mfma_f32_16x16x32_bf16 v[106:109], v[162:165], v[198:201], v[106:109]
	v_mfma_f32_16x16x32_bf16 v[102:105], v[154:157], v[198:201], v[102:105]
	v_mfma_f32_16x16x32_bf16 v[110:113], v[146:149], v[198:201], v[110:113]
	v_mfma_f32_16x16x32_bf16 v[94:97], v[146:149], v[206:209], v[94:97]
	v_mfma_f32_16x16x32_bf16 v[86:89], v[154:157], v[206:209], v[86:89]
	v_mfma_f32_16x16x32_bf16 v[90:93], v[162:165], v[206:209], v[90:93]
	v_mfma_f32_16x16x32_bf16 v[82:85], v[170:173], v[206:209], v[82:85]
	v_mfma_f32_16x16x32_bf16 v[66:69], v[170:173], v[232:235], v[66:69]
	v_mfma_f32_16x16x32_bf16 v[74:77], v[162:165], v[232:235], v[74:77]
	v_mfma_f32_16x16x32_bf16 v[70:73], v[154:157], v[232:235], v[70:73]
	v_mfma_f32_16x16x32_bf16 v[78:81], v[146:149], v[232:235], v[78:81]
	s_setprio 0
	s_setprio 1
	v_mfma_f32_16x16x32_bf16 v[126:129], v[150:153], v[194:197], v[126:129]
	v_mfma_f32_16x16x32_bf16 v[118:121], v[158:161], v[194:197], v[118:121]
	v_mfma_f32_16x16x32_bf16 v[122:125], v[166:169], v[194:197], v[122:125]
	v_mfma_f32_16x16x32_bf16 v[114:117], v[178:181], v[194:197], v[114:117]
	v_mfma_f32_16x16x32_bf16 v[98:101], v[178:181], v[202:205], v[98:101]
	v_mfma_f32_16x16x32_bf16 v[106:109], v[166:169], v[202:205], v[106:109]
	v_mfma_f32_16x16x32_bf16 v[102:105], v[158:161], v[202:205], v[102:105]
	v_mfma_f32_16x16x32_bf16 v[110:113], v[150:153], v[202:205], v[110:113]
	v_mfma_f32_16x16x32_bf16 v[94:97], v[150:153], v[228:231], v[94:97]
	v_mfma_f32_16x16x32_bf16 v[86:89], v[158:161], v[228:231], v[86:89]
	v_mfma_f32_16x16x32_bf16 v[90:93], v[166:169], v[228:231], v[90:93]
	v_mfma_f32_16x16x32_bf16 v[82:85], v[178:181], v[228:231], v[82:85]
	v_mfma_f32_16x16x32_bf16 v[66:69], v[178:181], v[236:239], v[66:69]
	v_mfma_f32_16x16x32_bf16 v[74:77], v[166:169], v[236:239], v[74:77]
	v_mfma_f32_16x16x32_bf16 v[70:73], v[158:161], v[236:239], v[70:73]
	v_mfma_f32_16x16x32_bf16 v[78:81], v[150:153], v[236:239], v[78:81]
	s_setprio 0
	s_barrier
	s_add_i32 s22, s53, s26
	v_lshl_add_u64 v[140:141], v[140:141], 0, s[34:35]
	s_mov_b32 m0, s22
	ds_read_b128 v[190:193], v145 offset:49152
	ds_read_b128 v[194:197], v145 offset:50176
	ds_read_b128 v[198:201], v145 offset:51200
	ds_read_b128 v[202:205], v145 offset:52224
	ds_read_b128 v[206:209], v145 offset:53248
	ds_read_b128 v[228:231], v145 offset:54272
	ds_read_b128 v[232:235], v145 offset:55296
	ds_read_b128 v[236:239], v145 offset:56320
	global_load_lds_dwordx4 v[140:141], off
	s_add_i32 m0, s22, 0x2000
	s_add_u32 s18, s18, 0x100080
	v_lshl_add_u64 v[140:141], v[186:187], 0, s[34:35]
	s_addc_u32 s19, s19, 0
	s_add_i32 s22, s54, s26
	global_load_lds_dwordx4 v[140:141], off
	v_lshl_add_u64 v[140:141], s[18:19], 0, v[0:1]
	s_mov_b32 m0, s22
	s_nop 0
	global_load_lds_dwordx4 v[140:141], off
	v_lshl_add_u64 v[140:141], s[18:19], 0, v[130:131]
	s_add_i32 m0, s22, 0x2000
	s_nop 0
	global_load_lds_dwordx4 v[140:141], off
	v_lshl_add_u64 v[140:141], v[188:189], 0, s[34:35]
	s_mov_b32 m0, s43
	s_nop 0
	global_load_lds_dwordx4 v[140:141], off
	v_lshl_add_u64 v[140:141], v[210:211], 0, s[34:35]
	s_mov_b32 m0, s44
	s_nop 0
	global_load_lds_dwordx4 v[140:141], off
	s_waitcnt vmcnt(8)
	s_waitcnt lgkmcnt(0)
	s_barrier
	s_setprio 1
	s_waitcnt lgkmcnt(0)
	v_mfma_f32_16x16x32_bf16 v[62:65], v[146:149], v[190:193], v[62:65]
	v_mfma_f32_16x16x32_bf16 v[54:57], v[154:157], v[190:193], v[54:57]
	v_mfma_f32_16x16x32_bf16 v[58:61], v[162:165], v[190:193], v[58:61]
	v_mfma_f32_16x16x32_bf16 v[50:53], v[170:173], v[190:193], v[50:53]
	v_mfma_f32_16x16x32_bf16 v[34:37], v[170:173], v[198:201], v[34:37]
	v_mfma_f32_16x16x32_bf16 v[42:45], v[162:165], v[198:201], v[42:45]
	v_mfma_f32_16x16x32_bf16 v[38:41], v[154:157], v[198:201], v[38:41]
	v_mfma_f32_16x16x32_bf16 v[46:49], v[146:149], v[198:201], v[46:49]
	v_mfma_f32_16x16x32_bf16 v[30:33], v[146:149], v[206:209], v[30:33]
	v_mfma_f32_16x16x32_bf16 v[22:25], v[154:157], v[206:209], v[22:25]
	v_mfma_f32_16x16x32_bf16 v[26:29], v[162:165], v[206:209], v[26:29]
	v_mfma_f32_16x16x32_bf16 v[18:21], v[170:173], v[206:209], v[18:21]
	v_mfma_f32_16x16x32_bf16 v[2:5], v[170:173], v[232:235], v[2:5]
	v_mfma_f32_16x16x32_bf16 v[10:13], v[162:165], v[232:235], v[10:13]
	v_mfma_f32_16x16x32_bf16 v[6:9], v[154:157], v[232:235], v[6:9]
	v_mfma_f32_16x16x32_bf16 v[14:17], v[146:149], v[232:235], v[14:17]
	s_setprio 0
	s_setprio 1
	v_mfma_f32_16x16x32_bf16 v[62:65], v[150:153], v[194:197], v[62:65]
	v_mfma_f32_16x16x32_bf16 v[54:57], v[158:161], v[194:197], v[54:57]
	v_mfma_f32_16x16x32_bf16 v[58:61], v[166:169], v[194:197], v[58:61]
	v_mfma_f32_16x16x32_bf16 v[50:53], v[178:181], v[194:197], v[50:53]
	v_mfma_f32_16x16x32_bf16 v[34:37], v[178:181], v[202:205], v[34:37]
	v_mfma_f32_16x16x32_bf16 v[42:45], v[166:169], v[202:205], v[42:45]
	v_mfma_f32_16x16x32_bf16 v[38:41], v[158:161], v[202:205], v[38:41]
	v_mfma_f32_16x16x32_bf16 v[46:49], v[150:153], v[202:205], v[46:49]
	v_mfma_f32_16x16x32_bf16 v[30:33], v[150:153], v[228:231], v[30:33]
	v_mfma_f32_16x16x32_bf16 v[22:25], v[158:161], v[228:231], v[22:25]
	v_mfma_f32_16x16x32_bf16 v[26:29], v[166:169], v[228:231], v[26:29]
	v_mfma_f32_16x16x32_bf16 v[18:21], v[178:181], v[228:231], v[18:21]
	v_mfma_f32_16x16x32_bf16 v[2:5], v[178:181], v[236:239], v[2:5]
	v_mfma_f32_16x16x32_bf16 v[10:13], v[166:169], v[236:239], v[10:13]
	v_mfma_f32_16x16x32_bf16 v[6:9], v[158:161], v[236:239], v[6:9]
	v_mfma_f32_16x16x32_bf16 v[14:17], v[150:153], v[236:239], v[14:17]
	s_setprio 0
	s_barrier
	s_add_i32 s52, s52, 2
	s_add_u32 s16, s16, 0x100
	s_addc_u32 s17, s17, 0
	s_add_u32 s50, s50, 0x100
	s_addc_u32 s51, s51, 0
	s_cmp_gt_u32 s52, 61
	s_cbranch_scc0 .LBB0_721
	s_and_b64 vcc, exec, s[2:3]
	s_cbranch_vccz .LBB0_724
	s_barrier

.LBB0_805:
	s_add_u32 s16, s14, 0x100
	s_addc_u32 s17, s15, 0
	s_add_i32 s49, 0, 0x10000
	s_cmpk_eq_i32 s48, 0xa8
	s_cselect_b32 s23, s5, s17
	s_cselect_b32 s22, s4, s16
	v_add_u32_e32 v140, s49, v143
	s_cselect_b32 s19, s9, s47
	s_cselect_b32 s18, s8, s46
	s_add_i32 s50, 0, 0x14000
	ds_read_b128 v[146:149], v140
	ds_read_b128 v[150:153], v140 offset:1024
	ds_read_b128 v[154:157], v140 offset:2048
	ds_read_b128 v[158:161], v140 offset:3072
	v_add_u32_e32 v140, s50, v143
	ds_read_b128 v[162:165], v140
	ds_read_b128 v[166:169], v140 offset:1024
	ds_read_b128 v[170:173], v140 offset:2048
	ds_read_b128 v[178:181], v140 offset:3072
	v_lshl_add_u64 v[140:141], s[14:15], 0, v[136:137]
	s_add_i32 m0, s31, 0xc000
	ds_read_b128 v[190:193], v145
	ds_read_b128 v[194:197], v145 offset:1024
	ds_read_b128 v[198:201], v145 offset:2048
	ds_read_b128 v[202:205], v145 offset:3072
	ds_read_b128 v[206:209], v145 offset:4096
	ds_read_b128 v[228:231], v145 offset:5120
	ds_read_b128 v[232:235], v145 offset:6144
	ds_read_b128 v[236:239], v145 offset:7168
	global_load_lds_dwordx4 v[140:141], off
	v_lshl_add_u64 v[140:141], s[14:15], 0, v[138:139]
	s_add_i32 m0, s31, 0xe000
	s_nop 0
	global_load_lds_dwordx4 v[140:141], off
	s_waitcnt vmcnt(8)
	s_waitcnt lgkmcnt(0)
	s_barrier
	s_setprio 1
	s_waitcnt lgkmcnt(0)
	v_mfma_f32_16x16x32_bf16 v[126:129], v[146:149], v[190:193], v[126:129]
	v_mfma_f32_16x16x32_bf16 v[122:125], v[154:157], v[190:193], v[122:125]
	v_mfma_f32_16x16x32_bf16 v[114:117], v[162:165], v[190:193], v[114:117]
	v_mfma_f32_16x16x32_bf16 v[106:109], v[170:173], v[190:193], v[106:109]
	v_mfma_f32_16x16x32_bf16 v[90:93], v[170:173], v[198:201], v[90:93]
	v_mfma_f32_16x16x32_bf16 v[98:101], v[162:165], v[198:201], v[98:101]
	v_mfma_f32_16x16x32_bf16 v[110:113], v[154:157], v[198:201], v[110:113]
	v_mfma_f32_16x16x32_bf16 v[118:121], v[146:149], v[198:201], v[118:121]
	v_mfma_f32_16x16x32_bf16 v[102:105], v[146:149], v[206:209], v[102:105]
	v_mfma_f32_16x16x32_bf16 v[94:97], v[154:157], v[206:209], v[94:97]
	v_mfma_f32_16x16x32_bf16 v[82:85], v[162:165], v[206:209], v[82:85]
	v_mfma_f32_16x16x32_bf16 v[74:77], v[170:173], v[206:209], v[74:77]
	v_mfma_f32_16x16x32_bf16 v[66:69], v[170:173], v[232:235], v[66:69]
	v_mfma_f32_16x16x32_bf16 v[70:73], v[162:165], v[232:235], v[70:73]
	v_mfma_f32_16x16x32_bf16 v[78:81], v[154:157], v[232:235], v[78:81]
	v_mfma_f32_16x16x32_bf16 v[86:89], v[146:149], v[232:235], v[86:89]
	s_setprio 0
	s_setprio 1
	v_mfma_f32_16x16x32_bf16 v[126:129], v[150:153], v[194:197], v[126:129]
	v_mfma_f32_16x16x32_bf16 v[122:125], v[158:161], v[194:197], v[122:125]
	v_mfma_f32_16x16x32_bf16 v[114:117], v[166:169], v[194:197], v[114:117]
	v_mfma_f32_16x16x32_bf16 v[106:109], v[178:181], v[194:197], v[106:109]
	v_mfma_f32_16x16x32_bf16 v[90:93], v[178:181], v[202:205], v[90:93]
	v_mfma_f32_16x16x32_bf16 v[98:101], v[166:169], v[202:205], v[98:101]
	v_mfma_f32_16x16x32_bf16 v[110:113], v[158:161], v[202:205], v[110:113]
	v_mfma_f32_16x16x32_bf16 v[118:121], v[150:153], v[202:205], v[118:121]
	v_mfma_f32_16x16x32_bf16 v[102:105], v[150:153], v[228:231], v[102:105]
	v_mfma_f32_16x16x32_bf16 v[94:97], v[158:161], v[228:231], v[94:97]
	v_mfma_f32_16x16x32_bf16 v[82:85], v[166:169], v[228:231], v[82:85]
	v_mfma_f32_16x16x32_bf16 v[74:77], v[178:181], v[228:231], v[74:77]
	v_mfma_f32_16x16x32_bf16 v[66:69], v[178:181], v[236:239], v[66:69]
	v_mfma_f32_16x16x32_bf16 v[70:73], v[166:169], v[236:239], v[70:73]
	v_mfma_f32_16x16x32_bf16 v[78:81], v[158:161], v[236:239], v[78:81]
	v_mfma_f32_16x16x32_bf16 v[86:89], v[150:153], v[236:239], v[86:89]
	s_setprio 0
	s_barrier
	s_add_i32 s14, s49, s26
	v_lshl_add_u64 v[140:141], s[18:19], 0, v[0:1]
	s_mov_b32 m0, s14
	ds_read_b128 v[190:193], v145 offset:16384
	ds_read_b128 v[194:197], v145 offset:17408
	ds_read_b128 v[198:201], v145 offset:18432
	ds_read_b128 v[202:205], v145 offset:19456
	ds_read_b128 v[206:209], v145 offset:20480
	ds_read_b128 v[228:231], v145 offset:21504
	ds_read_b128 v[232:235], v145 offset:22528
	ds_read_b128 v[236:239], v145 offset:23552
	global_load_lds_dwordx4 v[140:141], off
	s_add_i32 m0, s14, 0x2000
	s_add_u32 s14, s18, 0x2b0000
	v_lshl_add_u64 v[186:187], s[18:19], 0, v[130:131]
	s_addc_u32 s15, s19, 0
	s_add_i32 s49, s50, s26
	global_load_lds_dwordx4 v[186:187], off
	v_lshl_add_u64 v[188:189], s[14:15], 0, v[0:1]
	s_mov_b32 m0, s49
	v_lshl_add_u64 v[210:211], s[22:23], 0, v[132:133]
	global_load_lds_dwordx4 v[188:189], off
	v_lshl_add_u64 v[188:189], s[14:15], 0, v[130:131]
	s_add_i32 m0, s49, 0x2000
	s_nop 0
	global_load_lds_dwordx4 v[188:189], off
	v_lshl_add_u64 v[188:189], s[22:23], 0, v[134:135]
	s_mov_b32 m0, s31
	s_nop 0
	global_load_lds_dwordx4 v[188:189], off
	s_mov_b32 m0, s36
	s_nop 0
	global_load_lds_dwordx4 v[210:211], off
	s_waitcnt vmcnt(8)
	s_waitcnt lgkmcnt(0)
	s_barrier
	s_setprio 1
	s_waitcnt lgkmcnt(0)
	v_mfma_f32_16x16x32_bf16 v[62:65], v[146:149], v[190:193], v[62:65]
	v_mfma_f32_16x16x32_bf16 v[58:61], v[154:157], v[190:193], v[58:61]
	v_mfma_f32_16x16x32_bf16 v[50:53], v[162:165], v[190:193], v[50:53]
	v_mfma_f32_16x16x32_bf16 v[42:45], v[170:173], v[190:193], v[42:45]
	v_mfma_f32_16x16x32_bf16 v[26:29], v[170:173], v[198:201], v[26:29]
	v_mfma_f32_16x16x32_bf16 v[34:37], v[162:165], v[198:201], v[34:37]
	v_mfma_f32_16x16x32_bf16 v[46:49], v[154:157], v[198:201], v[46:49]
	v_mfma_f32_16x16x32_bf16 v[54:57], v[146:149], v[198:201], v[54:57]
	v_mfma_f32_16x16x32_bf16 v[38:41], v[146:149], v[206:209], v[38:41]
	v_mfma_f32_16x16x32_bf16 v[30:33], v[154:157], v[206:209], v[30:33]
	v_mfma_f32_16x16x32_bf16 v[18:21], v[162:165], v[206:209], v[18:21]
	v_mfma_f32_16x16x32_bf16 v[10:13], v[170:173], v[206:209], v[10:13]
	v_mfma_f32_16x16x32_bf16 v[2:5], v[170:173], v[232:235], v[2:5]
	v_mfma_f32_16x16x32_bf16 v[6:9], v[162:165], v[232:235], v[6:9]
	v_mfma_f32_16x16x32_bf16 v[14:17], v[154:157], v[232:235], v[14:17]
	v_mfma_f32_16x16x32_bf16 v[22:25], v[146:149], v[232:235], v[22:25]
	s_setprio 0
	s_setprio 1
	v_mfma_f32_16x16x32_bf16 v[62:65], v[150:153], v[194:197], v[62:65]
	v_mfma_f32_16x16x32_bf16 v[58:61], v[158:161], v[194:197], v[58:61]
	v_mfma_f32_16x16x32_bf16 v[50:53], v[166:169], v[194:197], v[50:53]
	v_mfma_f32_16x16x32_bf16 v[42:45], v[178:181], v[194:197], v[42:45]
	v_mfma_f32_16x16x32_bf16 v[26:29], v[178:181], v[202:205], v[26:29]
	v_mfma_f32_16x16x32_bf16 v[34:37], v[166:169], v[202:205], v[34:37]
	v_mfma_f32_16x16x32_bf16 v[46:49], v[158:161], v[202:205], v[46:49]
	v_mfma_f32_16x16x32_bf16 v[54:57], v[150:153], v[202:205], v[54:57]
	v_mfma_f32_16x16x32_bf16 v[38:41], v[150:153], v[228:231], v[38:41]
	v_mfma_f32_16x16x32_bf16 v[30:33], v[158:161], v[228:231], v[30:33]
	v_mfma_f32_16x16x32_bf16 v[18:21], v[166:169], v[228:231], v[18:21]
	v_mfma_f32_16x16x32_bf16 v[10:13], v[178:181], v[228:231], v[10:13]
	v_mfma_f32_16x16x32_bf16 v[2:5], v[178:181], v[236:239], v[2:5]
	v_mfma_f32_16x16x32_bf16 v[6:9], v[166:169], v[236:239], v[6:9]
	v_mfma_f32_16x16x32_bf16 v[14:17], v[158:161], v[236:239], v[14:17]
	v_mfma_f32_16x16x32_bf16 v[22:25], v[150:153], v[236:239], v[22:25]
	s_setprio 0
	s_barrier
	s_add_i32 s49, 0, 0x18000
	s_add_i32 s50, 0, 0x1c000
	v_add_u32_e32 v158, s49, v143
	v_add_u32_e32 v175, s50, v143
	ds_read_b128 v[146:149], v158
	ds_read_b128 v[150:153], v158 offset:1024
	ds_read_b128 v[154:157], v158 offset:2048
	ds_read_b128 v[158:161], v158 offset:3072
	ds_read_b128 v[162:165], v175
	ds_read_b128 v[166:169], v175 offset:1024
	ds_read_b128 v[170:173], v175 offset:2048
	ds_read_b128 v[178:181], v175 offset:3072
	s_add_u32 s14, s22, 0x2b0000
	s_addc_u32 s15, s23, 0
	s_mov_b32 m0, s37
	v_lshl_add_u64 v[226:227], s[14:15], 0, v[134:135]
	ds_read_b128 v[190:193], v145 offset:32768
	ds_read_b128 v[194:197], v145 offset:33792
	ds_read_b128 v[198:201], v145 offset:34816
	ds_read_b128 v[202:205], v145 offset:35840
	ds_read_b128 v[206:209], v145 offset:36864
	ds_read_b128 v[228:231], v145 offset:37888
	ds_read_b128 v[232:235], v145 offset:38912
	ds_read_b128 v[236:239], v145 offset:39936
	global_load_lds_dwordx4 v[226:227], off
	v_lshl_add_u64 v[226:227], s[14:15], 0, v[132:133]
	s_mov_b32 m0, s38
	s_nop 0
	global_load_lds_dwordx4 v[226:227], off
	s_waitcnt vmcnt(8)
	s_waitcnt lgkmcnt(0)
	s_barrier
	s_setprio 1
	s_waitcnt lgkmcnt(0)
	v_mfma_f32_16x16x32_bf16 v[126:129], v[146:149], v[190:193], v[126:129]
	v_mfma_f32_16x16x32_bf16 v[122:125], v[154:157], v[190:193], v[122:125]
	v_mfma_f32_16x16x32_bf16 v[114:117], v[162:165], v[190:193], v[114:117]
	v_mfma_f32_16x16x32_bf16 v[106:109], v[170:173], v[190:193], v[106:109]
	v_mfma_f32_16x16x32_bf16 v[90:93], v[170:173], v[198:201], v[90:93]
	v_mfma_f32_16x16x32_bf16 v[98:101], v[162:165], v[198:201], v[98:101]
	v_mfma_f32_16x16x32_bf16 v[110:113], v[154:157], v[198:201], v[110:113]
	v_mfma_f32_16x16x32_bf16 v[118:121], v[146:149], v[198:201], v[118:121]
	v_mfma_f32_16x16x32_bf16 v[102:105], v[146:149], v[206:209], v[102:105]
	v_mfma_f32_16x16x32_bf16 v[94:97], v[154:157], v[206:209], v[94:97]
	v_mfma_f32_16x16x32_bf16 v[82:85], v[162:165], v[206:209], v[82:85]
	v_mfma_f32_16x16x32_bf16 v[74:77], v[170:173], v[206:209], v[74:77]
	v_mfma_f32_16x16x32_bf16 v[66:69], v[170:173], v[232:235], v[66:69]
	v_mfma_f32_16x16x32_bf16 v[70:73], v[162:165], v[232:235], v[70:73]
	v_mfma_f32_16x16x32_bf16 v[78:81], v[154:157], v[232:235], v[78:81]
	v_mfma_f32_16x16x32_bf16 v[86:89], v[146:149], v[232:235], v[86:89]
	s_setprio 0
	s_setprio 1
	v_mfma_f32_16x16x32_bf16 v[126:129], v[150:153], v[194:197], v[126:129]
	v_mfma_f32_16x16x32_bf16 v[122:125], v[158:161], v[194:197], v[122:125]
	v_mfma_f32_16x16x32_bf16 v[114:117], v[166:169], v[194:197], v[114:117]
	v_mfma_f32_16x16x32_bf16 v[106:109], v[178:181], v[194:197], v[106:109]
	v_mfma_f32_16x16x32_bf16 v[90:93], v[178:181], v[202:205], v[90:93]
	v_mfma_f32_16x16x32_bf16 v[98:101], v[166:169], v[202:205], v[98:101]
	v_mfma_f32_16x16x32_bf16 v[110:113], v[158:161], v[202:205], v[110:113]
	v_mfma_f32_16x16x32_bf16 v[118:121], v[150:153], v[202:205], v[118:121]
	v_mfma_f32_16x16x32_bf16 v[102:105], v[150:153], v[228:231], v[102:105]
	v_mfma_f32_16x16x32_bf16 v[94:97], v[158:161], v[228:231], v[94:97]
	v_mfma_f32_16x16x32_bf16 v[82:85], v[166:169], v[228:231], v[82:85]
	v_mfma_f32_16x16x32_bf16 v[74:77], v[178:181], v[228:231], v[74:77]
	v_mfma_f32_16x16x32_bf16 v[66:69], v[178:181], v[236:239], v[66:69]
	v_mfma_f32_16x16x32_bf16 v[70:73], v[166:169], v[236:239], v[70:73]
	v_mfma_f32_16x16x32_bf16 v[78:81], v[158:161], v[236:239], v[78:81]
	v_mfma_f32_16x16x32_bf16 v[86:89], v[150:153], v[236:239], v[86:89]
	s_setprio 0
	s_barrier
	s_add_i32 s14, s49, s26
	v_lshl_add_u64 v[140:141], v[140:141], 0, s[34:35]
	s_mov_b32 m0, s14
	ds_read_b128 v[190:193], v145 offset:49152
	ds_read_b128 v[194:197], v145 offset:50176
	ds_read_b128 v[198:201], v145 offset:51200
	ds_read_b128 v[202:205], v145 offset:52224
	ds_read_b128 v[206:209], v145 offset:53248
	ds_read_b128 v[228:231], v145 offset:54272
	ds_read_b128 v[232:235], v145 offset:55296
	ds_read_b128 v[236:239], v145 offset:56320
	global_load_lds_dwordx4 v[140:141], off
	s_add_i32 m0, s14, 0x2000
	s_add_u32 s14, s18, 0x2b0080
	v_lshl_add_u64 v[140:141], v[186:187], 0, s[34:35]
	s_addc_u32 s15, s19, 0
	s_add_i32 s18, s50, s26
	global_load_lds_dwordx4 v[140:141], off
	v_lshl_add_u64 v[140:141], s[14:15], 0, v[0:1]
	s_mov_b32 m0, s18
	s_nop 0
	global_load_lds_dwordx4 v[140:141], off
	v_lshl_add_u64 v[140:141], s[14:15], 0, v[130:131]
	s_add_i32 m0, s18, 0x2000
	s_nop 0
	global_load_lds_dwordx4 v[140:141], off
	v_lshl_add_u64 v[140:141], v[188:189], 0, s[34:35]
	s_mov_b32 m0, s39
	s_nop 0
	global_load_lds_dwordx4 v[140:141], off
	v_lshl_add_u64 v[140:141], v[210:211], 0, s[34:35]
	s_mov_b32 m0, s40
	s_nop 0
	global_load_lds_dwordx4 v[140:141], off
	s_waitcnt vmcnt(8)
	s_waitcnt lgkmcnt(0)
	s_barrier
	s_setprio 1
	s_waitcnt lgkmcnt(0)
	v_mfma_f32_16x16x32_bf16 v[62:65], v[146:149], v[190:193], v[62:65]
	v_mfma_f32_16x16x32_bf16 v[58:61], v[154:157], v[190:193], v[58:61]
	v_mfma_f32_16x16x32_bf16 v[50:53], v[162:165], v[190:193], v[50:53]
	v_mfma_f32_16x16x32_bf16 v[42:45], v[170:173], v[190:193], v[42:45]
	v_mfma_f32_16x16x32_bf16 v[26:29], v[170:173], v[198:201], v[26:29]
	v_mfma_f32_16x16x32_bf16 v[34:37], v[162:165], v[198:201], v[34:37]
	v_mfma_f32_16x16x32_bf16 v[46:49], v[154:157], v[198:201], v[46:49]
	v_mfma_f32_16x16x32_bf16 v[54:57], v[146:149], v[198:201], v[54:57]
	v_mfma_f32_16x16x32_bf16 v[38:41], v[146:149], v[206:209], v[38:41]
	v_mfma_f32_16x16x32_bf16 v[30:33], v[154:157], v[206:209], v[30:33]
	v_mfma_f32_16x16x32_bf16 v[18:21], v[162:165], v[206:209], v[18:21]
	v_mfma_f32_16x16x32_bf16 v[10:13], v[170:173], v[206:209], v[10:13]
	v_mfma_f32_16x16x32_bf16 v[2:5], v[170:173], v[232:235], v[2:5]
	v_mfma_f32_16x16x32_bf16 v[6:9], v[162:165], v[232:235], v[6:9]
	v_mfma_f32_16x16x32_bf16 v[14:17], v[154:157], v[232:235], v[14:17]
	v_mfma_f32_16x16x32_bf16 v[22:25], v[146:149], v[232:235], v[22:25]
	s_setprio 0
	s_setprio 1
	v_mfma_f32_16x16x32_bf16 v[62:65], v[150:153], v[194:197], v[62:65]
	v_mfma_f32_16x16x32_bf16 v[58:61], v[158:161], v[194:197], v[58:61]
	v_mfma_f32_16x16x32_bf16 v[50:53], v[166:169], v[194:197], v[50:53]
	v_mfma_f32_16x16x32_bf16 v[42:45], v[178:181], v[194:197], v[42:45]
	v_mfma_f32_16x16x32_bf16 v[26:29], v[178:181], v[202:205], v[26:29]
	v_mfma_f32_16x16x32_bf16 v[34:37], v[166:169], v[202:205], v[34:37]
	v_mfma_f32_16x16x32_bf16 v[46:49], v[158:161], v[202:205], v[46:49]
	v_mfma_f32_16x16x32_bf16 v[54:57], v[150:153], v[202:205], v[54:57]
	v_mfma_f32_16x16x32_bf16 v[38:41], v[150:153], v[228:231], v[38:41]
	v_mfma_f32_16x16x32_bf16 v[30:33], v[158:161], v[228:231], v[30:33]
	v_mfma_f32_16x16x32_bf16 v[18:21], v[166:169], v[228:231], v[18:21]
	v_mfma_f32_16x16x32_bf16 v[10:13], v[178:181], v[228:231], v[10:13]
	v_mfma_f32_16x16x32_bf16 v[2:5], v[178:181], v[236:239], v[2:5]
	v_mfma_f32_16x16x32_bf16 v[6:9], v[166:169], v[236:239], v[6:9]
	v_mfma_f32_16x16x32_bf16 v[14:17], v[158:161], v[236:239], v[14:17]
	v_mfma_f32_16x16x32_bf16 v[22:25], v[150:153], v[236:239], v[22:25]
	s_setprio 0
	s_barrier
	s_add_i32 s48, s48, 2
	s_add_u32 s46, s46, 0x100
	s_addc_u32 s47, s47, 0
	s_cmpk_gt_u32 s48, 0xa9
	s_mov_b64 s[14:15], s[16:17]
	s_cbranch_scc0 .LBB0_805
	s_and_b64 vcc, exec, s[6:7]
	s_cbranch_vccz .LBB0_808
	s_barrier
